# weight-conversion prologue: LDS transpose reads issued in batches with counted waits instead of one round trip per pair
# baseline (speedup 1.0000x reference)
.LBB0_11:
	s_cmpk_gt_i32 s50, 0x3ff
	s_mov_b64 s[4:5], -1
	s_cbranch_scc0 .LBB0_101
	s_cmpk_gt_u32 s50, 0x5ff
	s_cbranch_scc0 .LBB0_98
	s_cmpk_gt_u32 s50, 0x10ff
	s_cbranch_scc0 .LBB0_87
	s_cmpk_gt_u32 s50, 0x167f
	s_cbranch_scc0 .LBB0_84
	s_cmpk_gt_u32 s50, 0x197f
	s_cbranch_scc0 .LBB0_57
	s_cmpk_gt_u32 s50, 0x1f7f
	s_cbranch_scc0 .LBB0_38
	s_cmpk_gt_u32 s50, 0x217f
	s_cbranch_scc0 .LBB0_35
	s_cmpk_gt_u32 s50, 0x2c7f
	s_cbranch_scc0 .LBB0_24
	s_cmpk_gt_u32 s50, 0x31ff
	s_cbranch_scc0 .LBB0_21
	s_add_i32 s4, s50, 0xffffce00
	s_cmp_lt_u32 s4, 64
	s_cselect_b32 s4, 48, 64
	s_add_u32 s4, s0, s4
	s_addc_u32 s5, s1, 0
	s_load_dwordx2 s[4:5], s[4:5], 0x0
	s_lshl_b32 s14, s50, 13
	s_and_b32 s26, s14, 0x70000
	v_mov_b32_e32 v73, v37
	v_add_u32_e32 v75, 0x848, v87
	s_waitcnt lgkmcnt(0)
	s_add_u32 s14, s4, s26
	s_addc_u32 s5, s5, 0
	s_add_i32 s4, s35, 0xffff9c00
	s_and_b32 s15, s9, 0x60
	s_and_b32 s4, s4, 0x7fffff80
	s_or_b32 s4, s4, s15
	s_and_b32 s51, s37, 64
	s_lshl_b32 s15, s15, 2
	s_add_u32 s14, s14, s15
	v_or_b32_e32 v4, s51, v1
	s_addc_u32 s15, s5, 0
	v_lshl_add_u64 v[2:3], s[14:15], 0, v[72:73]
	v_lshlrev_b32_e32 v36, 9, v4
	v_lshl_add_u64 v[30:31], v[2:3], 0, v[36:37]
	v_add_co_u32_e32 v10, vcc, s39, v30
	global_load_dwordx4 v[2:5], v[30:31], off nt
	s_nop 0
	v_addc_co_u32_e32 v11, vcc, 0, v31, vcc
	v_add_co_u32_e32 v18, vcc, s42, v30
	global_load_dwordx4 v[6:9], v[10:11], off offset:-4096 nt
	s_nop 0
	global_load_dwordx4 v[10:13], v[10:11], off nt
	v_addc_co_u32_e32 v19, vcc, 0, v31, vcc
	v_add_co_u32_e32 v26, vcc, s43, v30
	global_load_dwordx4 v[14:17], v[18:19], off offset:-4096 nt
	s_nop 0
	global_load_dwordx4 v[18:21], v[18:19], off nt
	v_addc_co_u32_e32 v27, vcc, 0, v31, vcc
	v_add_co_u32_e32 v30, vcc, s46, v30
	global_load_dwordx4 v[22:25], v[26:27], off offset:-4096 nt
	s_nop 0
	global_load_dwordx4 v[26:29], v[26:27], off nt
	v_addc_co_u32_e32 v31, vcc, 0, v31, vcc
	global_load_dwordx4 v[30:33], v[30:31], off nt
	v_add_u32_e32 v36, 0x428, v87
	v_add_u32_e32 v73, 0x840, v87
	v_add_u32_e32 v76, 0xc60, v87
	v_add_u32_e32 v89, 0xc68, v87
	v_add_u32_e32 v90, 0x1080, v87
	v_add_u32_e32 v91, 0x1088, v87
	v_add_u32_e32 v92, 0x14a0, v87
	v_add_u32_e32 v93, 0x14a8, v87
	v_add_u32_e32 v94, 0x18c0, v87
	v_add_u32_e32 v95, 0x18c8, v87
	v_add_u32_e32 v96, 0x1ce0, v87
	v_add_u32_e32 v97, 0x1ce8, v87
	s_waitcnt vmcnt(7)
	v_pk_mul_f32 v[2:3], v[2:3], s[8:9] op_sel_hi:[1,0]
	v_pk_mul_f32 v[4:5], v[4:5], s[8:9] op_sel_hi:[1,0]
	ds_write2_b32 v87, v2, v3 offset1:1
	ds_write2_b32 v87, v4, v5 offset0:2 offset1:3
	s_waitcnt vmcnt(6)
	v_pk_mul_f32 v[2:3], v[6:7], s[8:9] op_sel_hi:[1,0]
	v_pk_mul_f32 v[4:5], v[8:9], s[8:9] op_sel_hi:[1,0]
	s_waitcnt vmcnt(5)
	v_pk_mul_f32 v[6:7], v[10:11], s[8:9] op_sel_hi:[1,0]
	v_pk_mul_f32 v[8:9], v[12:13], s[8:9] op_sel_hi:[1,0]
	s_waitcnt vmcnt(4)
	v_pk_mul_f32 v[10:11], v[14:15], s[8:9] op_sel_hi:[1,0]
	v_pk_mul_f32 v[12:13], v[16:17], s[8:9] op_sel_hi:[1,0]
	s_waitcnt vmcnt(3)
	v_pk_mul_f32 v[14:15], v[18:19], s[8:9] op_sel_hi:[1,0]
	v_pk_mul_f32 v[16:17], v[20:21], s[8:9] op_sel_hi:[1,0]
	s_waitcnt vmcnt(2)
	v_pk_mul_f32 v[18:19], v[22:23], s[8:9] op_sel_hi:[1,0]
	v_pk_mul_f32 v[20:21], v[24:25], s[8:9] op_sel_hi:[1,0]
	s_waitcnt vmcnt(1)
	v_pk_mul_f32 v[22:23], v[26:27], s[8:9] op_sel_hi:[1,0]
	v_pk_mul_f32 v[24:25], v[28:29], s[8:9] op_sel_hi:[1,0]
	s_waitcnt vmcnt(0)
	v_pk_mul_f32 v[26:27], v[30:31], s[8:9] op_sel_hi:[1,0]
	v_pk_mul_f32 v[28:29], v[32:33], s[8:9] op_sel_hi:[1,0]
	ds_write2_b32 v88, v2, v3 offset1:1
	ds_write2_b32 v36, v4, v5 offset1:1
	ds_write2_b32 v73, v6, v7 offset1:1
	ds_write2_b32 v75, v8, v9 offset1:1
	ds_write2_b32 v76, v10, v11 offset1:1
	ds_write2_b32 v89, v12, v13 offset1:1
	ds_write2_b32 v90, v14, v15 offset1:1
	ds_write2_b32 v91, v16, v17 offset1:1
	ds_write2_b32 v92, v18, v19 offset1:1
	ds_write2_b32 v93, v20, v21 offset1:1
	ds_write2_b32 v94, v22, v23 offset1:1
	ds_write2_b32 v95, v24, v25 offset1:1
	ds_write2_b32 v96, v26, v27 offset1:1
	ds_write2_b32 v97, v28, v29 offset1:1
	s_waitcnt lgkmcnt(0)
	v_lshl_add_u64 v[8:9], v[34:35], 0, s[26:27]
	s_lshl_b32 s26, s51, 1
	ds_read2_b32 v[12:13], v80 offset1:33
	ds_read2_b32 v[14:15], v80 offset0:66 offset1:99
	ds_read2_b32 v[16:17], v80 offset0:132 offset1:165
	ds_read2_b32 v[18:19], v80 offset0:198 offset1:231
	ds_read2_b32 v[20:21], v80 offset0:8 offset1:41
	ds_read2_b32 v[22:23], v80 offset0:74 offset1:107
	ds_read2_b32 v[24:25], v80 offset0:140 offset1:173
	ds_read2_b32 v[26:27], v80 offset0:206 offset1:239
	s_waitcnt lgkmcnt(7)
	v_cvt_pk_bf16_f32 v2, v12, v13
	v_mov_b32_e32 v75, v37
	v_lshl_add_u64 v[8:9], v[8:9], 0, s[26:27]
	v_or_b32_e32 v36, s4, v1
	ds_read2_b32 v[12:13], v80 offset0:16 offset1:49
	s_waitcnt lgkmcnt(7)
	v_cvt_pk_bf16_f32 v3, v14, v15
	v_lshl_add_u64 v[8:9], v[8:9], 0, v[74:75]
	v_lshlrev_b64 v[10:11], 8, v[36:37]
	ds_read2_b32 v[14:15], v80 offset0:82 offset1:115
	s_waitcnt lgkmcnt(7)
	v_cvt_pk_bf16_f32 v4, v16, v17
	ds_read2_b32 v[16:17], v80 offset0:148 offset1:181
	s_waitcnt lgkmcnt(7)
	v_cvt_pk_bf16_f32 v5, v18, v19
	v_lshl_add_u64 v[10:11], v[8:9], 0, v[10:11]
	global_store_dwordx4 v[10:11], v[2:5], off
	v_or_b32_e32 v36, s4, v77
	v_lshlrev_b64 v[10:11], 8, v[36:37]
	ds_read2_b32 v[18:19], v80 offset0:214 offset1:247
	s_waitcnt lgkmcnt(7)
	v_cvt_pk_bf16_f32 v2, v20, v21
	ds_read2_b32 v[20:21], v80 offset0:24 offset1:57
	s_waitcnt lgkmcnt(7)
	v_cvt_pk_bf16_f32 v3, v22, v23
	ds_read2_b32 v[22:23], v80 offset0:90 offset1:123
	s_waitcnt lgkmcnt(7)
	v_cvt_pk_bf16_f32 v4, v24, v25
	ds_read2_b32 v[24:25], v80 offset0:156 offset1:189
	s_waitcnt lgkmcnt(7)
	v_cvt_pk_bf16_f32 v5, v26, v27
	v_lshl_add_u64 v[10:11], v[8:9], 0, v[10:11]
	global_store_dwordx4 v[10:11], v[2:5], off
	v_or_b32_e32 v36, s4, v78
	v_lshlrev_b64 v[10:11], 8, v[36:37]
	ds_read2_b32 v[26:27], v80 offset0:222 offset1:255
	s_waitcnt lgkmcnt(7)
	v_cvt_pk_bf16_f32 v2, v12, v13
	s_waitcnt lgkmcnt(6)
	v_cvt_pk_bf16_f32 v3, v14, v15
	s_waitcnt lgkmcnt(5)
	v_cvt_pk_bf16_f32 v4, v16, v17
	s_waitcnt lgkmcnt(4)
	v_cvt_pk_bf16_f32 v5, v18, v19
	v_lshl_add_u64 v[10:11], v[8:9], 0, v[10:11]
	global_store_dwordx4 v[10:11], v[2:5], off
	v_or_b32_e32 v36, s4, v79
	v_lshlrev_b64 v[10:11], 8, v[36:37]
	s_waitcnt lgkmcnt(3)
	v_cvt_pk_bf16_f32 v2, v20, v21
	s_waitcnt lgkmcnt(2)
	v_cvt_pk_bf16_f32 v3, v22, v23
	s_waitcnt lgkmcnt(1)
	v_cvt_pk_bf16_f32 v4, v24, v25
	s_waitcnt lgkmcnt(0)
	v_cvt_pk_bf16_f32 v5, v26, v27
	v_lshl_add_u64 v[6:7], v[8:9], 0, v[10:11]
	global_store_dwordx4 v[6:7], v[2:5], off
	s_waitcnt lgkmcnt(0)
	s_mov_b64 s[4:5], 0
.LBB0_21:
	s_andn2_b64 vcc, exec, s[4:5]
	s_cbranch_vccnz .LBB0_23
	s_and_b32 s4, s35, 0x7fc0
	s_addk_i32 s4, 0xa700
	s_and_b32 s14, s9, 0x3e0
	v_or_b32_e32 v36, s4, v1
	s_lshl_b32 s26, s14, 2
	v_or_b32_e32 v4, 8, v36
	v_mov_b32_e32 v5, v37
	v_or_b32_e32 v10, 16, v36
	v_mov_b32_e32 v11, v37
	v_or_b32_e32 v12, 24, v36
	v_mov_b32_e32 v13, v37
	v_or_b32_e32 v18, 32, v36
	v_mov_b32_e32 v19, v37
	v_or_b32_e32 v20, 40, v36
	v_mov_b32_e32 v21, v37
	v_lshl_add_u64 v[30:31], v[54:55], 0, s[26:27]
	v_lshlrev_b64 v[2:3], 12, v[36:37]
	v_lshlrev_b64 v[4:5], 12, v[4:5]
	v_lshlrev_b64 v[10:11], 12, v[10:11]
	v_lshlrev_b64 v[12:13], 12, v[12:13]
	v_lshlrev_b64 v[18:19], 12, v[18:19]
	v_lshlrev_b64 v[20:21], 12, v[20:21]
	v_lshl_add_u64 v[2:3], v[30:31], 0, v[2:3]
	v_lshl_add_u64 v[6:7], v[30:31], 0, v[4:5]
	v_lshl_add_u64 v[10:11], v[30:31], 0, v[10:11]
	v_lshl_add_u64 v[14:15], v[30:31], 0, v[12:13]
	v_lshl_add_u64 v[18:19], v[30:31], 0, v[18:19]
	v_lshl_add_u64 v[22:23], v[30:31], 0, v[20:21]
	global_load_dwordx4 v[2:5], v[2:3], off nt
	s_nop 0
	global_load_dwordx4 v[6:9], v[6:7], off nt
	s_nop 0
	global_load_dwordx4 v[10:13], v[10:11], off nt
	s_nop 0
	global_load_dwordx4 v[14:17], v[14:15], off nt
	s_nop 0
	global_load_dwordx4 v[18:21], v[18:19], off nt
	s_nop 0
	global_load_dwordx4 v[22:25], v[22:23], off nt
	v_or_b32_e32 v26, 48, v36
	v_mov_b32_e32 v27, v37
	v_lshlrev_b64 v[26:27], 12, v[26:27]
	v_lshl_add_u64 v[26:27], v[30:31], 0, v[26:27]
	v_or_b32_e32 v36, 56, v36
	global_load_dwordx4 v[26:29], v[26:27], off nt
	v_lshlrev_b64 v[32:33], 12, v[36:37]
	v_lshl_add_u64 v[30:31], v[30:31], 0, v[32:33]
	global_load_dwordx4 v[30:33], v[30:31], off nt
	v_add_u32_e32 v36, 0x428, v87
	v_add_u32_e32 v73, 0x840, v87
	v_add_u32_e32 v75, 0x848, v87
	v_add_u32_e32 v76, 0xc60, v87
	v_add_u32_e32 v89, 0xc68, v87
	v_add_u32_e32 v90, 0x1080, v87
	v_add_u32_e32 v91, 0x1088, v87
	v_add_u32_e32 v92, 0x14a0, v87
	v_add_u32_e32 v93, 0x14a8, v87
	v_add_u32_e32 v94, 0x18c0, v87
	v_add_u32_e32 v95, 0x18c8, v87
	v_add_u32_e32 v96, 0x1ce0, v87
	v_add_u32_e32 v97, 0x1ce8, v87
	s_mov_b32 s5, s27
	s_waitcnt vmcnt(7)
	ds_write2_b32 v87, v2, v3 offset1:1
	ds_write2_b32 v87, v4, v5 offset0:2 offset1:3
	s_waitcnt vmcnt(6)
	ds_write2_b32 v88, v6, v7 offset1:1
	ds_write2_b32 v36, v8, v9 offset1:1
	s_waitcnt vmcnt(5)
	ds_write2_b32 v73, v10, v11 offset1:1
	ds_write2_b32 v75, v12, v13 offset1:1
	s_waitcnt vmcnt(4)
	ds_write2_b32 v76, v14, v15 offset1:1
	ds_write2_b32 v89, v16, v17 offset1:1
	s_waitcnt vmcnt(3)
	ds_write2_b32 v90, v18, v19 offset1:1
	ds_write2_b32 v91, v20, v21 offset1:1
	s_waitcnt vmcnt(2)
	ds_write2_b32 v92, v22, v23 offset1:1
	ds_write2_b32 v93, v24, v25 offset1:1
	s_waitcnt vmcnt(1)
	ds_write2_b32 v94, v26, v27 offset1:1
	ds_write2_b32 v95, v28, v29 offset1:1
	s_waitcnt vmcnt(0)
	ds_write2_b32 v96, v30, v31 offset1:1
	ds_write2_b32 v97, v32, v33 offset1:1
	s_waitcnt lgkmcnt(0)
	v_or_b32_e32 v10, s14, v1
	v_mul_u32_u24_e32 v10, 0xb00, v10
	ds_read2_b32 v[12:13], v80 offset1:33
	ds_read2_b32 v[14:15], v80 offset0:66 offset1:99
	ds_read2_b32 v[16:17], v80 offset0:132 offset1:165
	ds_read2_b32 v[18:19], v80 offset0:198 offset1:231
	ds_read2_b32 v[20:21], v80 offset0:8 offset1:41
	ds_read2_b32 v[22:23], v80 offset0:74 offset1:107
	ds_read2_b32 v[24:25], v80 offset0:140 offset1:173
	ds_read2_b32 v[26:27], v80 offset0:206 offset1:239
	s_waitcnt lgkmcnt(7)
	v_cvt_pk_bf16_f32 v2, v12, v13
	v_lshl_add_u64 v[8:9], s[4:5], 1, v[38:39]
	v_lshlrev_b32_e32 v36, 1, v10
	ds_read2_b32 v[12:13], v80 offset0:16 offset1:49
	s_waitcnt lgkmcnt(7)
	v_cvt_pk_bf16_f32 v3, v14, v15
	v_lshl_add_u64 v[10:11], v[8:9], 0, v[36:37]
	ds_read2_b32 v[14:15], v80 offset0:82 offset1:115
	s_waitcnt lgkmcnt(7)
	v_cvt_pk_bf16_f32 v4, v16, v17
	ds_read2_b32 v[16:17], v80 offset0:148 offset1:181
	s_waitcnt lgkmcnt(7)
	v_cvt_pk_bf16_f32 v5, v18, v19
	global_store_dwordx4 v[10:11], v[2:5], off
	v_or_b32_e32 v10, s14, v77
	v_mul_u32_u24_e32 v10, 0xb00, v10
	ds_read2_b32 v[18:19], v80 offset0:214 offset1:247
	s_waitcnt lgkmcnt(7)
	v_cvt_pk_bf16_f32 v2, v20, v21
	v_lshlrev_b32_e32 v36, 1, v10
	ds_read2_b32 v[20:21], v80 offset0:24 offset1:57
	s_waitcnt lgkmcnt(7)
	v_cvt_pk_bf16_f32 v3, v22, v23
	v_lshl_add_u64 v[10:11], v[8:9], 0, v[36:37]
	ds_read2_b32 v[22:23], v80 offset0:90 offset1:123
	s_waitcnt lgkmcnt(7)
	v_cvt_pk_bf16_f32 v4, v24, v25
	ds_read2_b32 v[24:25], v80 offset0:156 offset1:189
	s_waitcnt lgkmcnt(7)
	v_cvt_pk_bf16_f32 v5, v26, v27
	global_store_dwordx4 v[10:11], v[2:5], off
	v_or_b32_e32 v10, s14, v78
	ds_read2_b32 v[26:27], v80 offset0:222 offset1:255
	s_waitcnt lgkmcnt(7)
	v_cvt_pk_bf16_f32 v2, v12, v13
	v_mul_u32_u24_e32 v10, 0xb00, v10
	s_waitcnt lgkmcnt(6)
	v_cvt_pk_bf16_f32 v3, v14, v15
	v_lshlrev_b32_e32 v36, 1, v10
	s_waitcnt lgkmcnt(5)
	v_cvt_pk_bf16_f32 v4, v16, v17
	s_waitcnt lgkmcnt(4)
	v_cvt_pk_bf16_f32 v5, v18, v19
	v_lshl_add_u64 v[10:11], v[8:9], 0, v[36:37]
	global_store_dwordx4 v[10:11], v[2:5], off
	s_nop 0
	s_waitcnt lgkmcnt(3)
	v_cvt_pk_bf16_f32 v2, v20, v21
	s_waitcnt lgkmcnt(2)
	v_cvt_pk_bf16_f32 v3, v22, v23
	s_waitcnt lgkmcnt(1)
	v_cvt_pk_bf16_f32 v4, v24, v25
	v_or_b32_e32 v5, s14, v79
	v_mul_u32_u24_e32 v5, 0xb00, v5
	v_lshlrev_b32_e32 v36, 1, v5
	s_waitcnt lgkmcnt(0)
	v_cvt_pk_bf16_f32 v5, v26, v27
	v_lshl_add_u64 v[6:7], v[8:9], 0, v[36:37]
	global_store_dwordx4 v[6:7], v[2:5], off
	s_waitcnt lgkmcnt(0)

.LBB0_33:
	s_lshl_b32 s4, s15, 5
	s_and_b32 s5, 0xffff, s15
	s_add_i32 s15, s4, 0xf500
	s_cmpk_lt_u32 s5, 0x58
	s_cselect_b32 s4, s4, s15
	s_sext_i32_i16 s5, s4
	s_cselect_b32 s15, 0, 0x80
	s_bfe_u32 s5, s5, 0x70018
	v_add_u32_e32 v10, 0x18c0, v87
	s_add_i32 s5, s4, s5
	ds_write2_b32 v10, v6, v7 offset1:1
	v_add_u32_e32 v6, 0x18c8, v87
	s_sext_i32_i16 s26, s5
	s_and_b32 s5, s5, 0xff80
	ds_write2_b32 v6, v8, v9 offset1:1
	s_waitcnt vmcnt(0)
	v_pk_mul_f32 v[2:3], v[2:3], v[18:19] op_sel_hi:[1,0]
	v_add_u32_e32 v6, 0x1ce0, v87
	s_sub_i32 s4, s4, s5
	ds_write2_b32 v6, v2, v3 offset1:1
	v_pk_mul_f32 v[2:3], v[4:5], v[18:19] op_sel_hi:[1,0]
	v_add_u32_e32 v4, 0x1ce8, v87
	s_lshl_b32 s26, s26, 1
	s_sext_i32_i16 s4, s4
	ds_write2_b32 v4, v2, v3 offset1:1
	s_and_b32 s26, s26, 0xffffff00
	s_add_i32 s4, s15, s4
	s_waitcnt lgkmcnt(0)
	s_add_i32 s4, s4, s26
	s_and_b32 s5, 0xffff, s14
	v_add_u32_e32 v10, s4, v1
	ds_read2_b32 v[12:13], v80 offset1:33
	ds_read2_b32 v[14:15], v80 offset0:66 offset1:99
	ds_read2_b32 v[16:17], v80 offset0:132 offset1:165
	ds_read2_b32 v[18:19], v80 offset0:198 offset1:231
	ds_read2_b32 v[20:21], v80 offset0:8 offset1:41
	ds_read2_b32 v[22:23], v80 offset0:74 offset1:107
	ds_read2_b32 v[24:25], v80 offset0:140 offset1:173
	ds_read2_b32 v[26:27], v80 offset0:206 offset1:239
	s_waitcnt lgkmcnt(7)
	v_cvt_pk_bf16_f32 v2, v12, v13
	s_lshl_b32 s26, s5, 1
	v_ashrrev_i32_e32 v11, 31, v10
	ds_read2_b32 v[12:13], v80 offset0:16 offset1:49
	s_waitcnt lgkmcnt(7)
	v_cvt_pk_bf16_f32 v3, v14, v15
	v_lshl_add_u64 v[8:9], v[40:41], 0, s[26:27]
	v_lshlrev_b64 v[10:11], 11, v[10:11]
	ds_read2_b32 v[14:15], v80 offset0:82 offset1:115
	s_waitcnt lgkmcnt(7)
	v_cvt_pk_bf16_f32 v4, v16, v17
	ds_read2_b32 v[16:17], v80 offset0:148 offset1:181
	s_waitcnt lgkmcnt(7)
	v_cvt_pk_bf16_f32 v5, v18, v19
	v_lshl_add_u64 v[10:11], v[8:9], 0, v[10:11]
	global_store_dwordx4 v[10:11], v[2:5], off
	s_nop 0
	ds_read2_b32 v[18:19], v80 offset0:214 offset1:247
	s_waitcnt lgkmcnt(7)
	v_cvt_pk_bf16_f32 v2, v20, v21
	ds_read2_b32 v[20:21], v80 offset0:24 offset1:57
	s_waitcnt lgkmcnt(7)
	v_cvt_pk_bf16_f32 v3, v22, v23
	ds_read2_b32 v[22:23], v80 offset0:90 offset1:123
	s_waitcnt lgkmcnt(7)
	v_cvt_pk_bf16_f32 v4, v24, v25
	ds_read2_b32 v[24:25], v80 offset0:156 offset1:189
	s_waitcnt lgkmcnt(7)
	v_cvt_pk_bf16_f32 v5, v26, v27
	v_add_u32_e32 v6, s4, v77
	v_ashrrev_i32_e32 v7, 31, v6
	v_lshlrev_b64 v[6:7], 11, v[6:7]
	v_lshl_add_u64 v[6:7], v[8:9], 0, v[6:7]
	global_store_dwordx4 v[6:7], v[2:5], off
	s_nop 0
	ds_read2_b32 v[26:27], v80 offset0:222 offset1:255
	s_waitcnt lgkmcnt(7)
	v_cvt_pk_bf16_f32 v2, v12, v13
	s_waitcnt lgkmcnt(6)
	v_cvt_pk_bf16_f32 v3, v14, v15
	s_waitcnt lgkmcnt(5)
	v_cvt_pk_bf16_f32 v4, v16, v17
	s_waitcnt lgkmcnt(4)
	v_cvt_pk_bf16_f32 v5, v18, v19
	v_add_u32_e32 v6, s4, v78
	v_ashrrev_i32_e32 v7, 31, v6
	v_lshlrev_b64 v[6:7], 11, v[6:7]
	v_lshl_add_u64 v[6:7], v[8:9], 0, v[6:7]
	global_store_dwordx4 v[6:7], v[2:5], off
	s_nop 0
	s_waitcnt lgkmcnt(3)
	v_cvt_pk_bf16_f32 v2, v20, v21
	v_add_u32_e32 v10, s4, v79
	s_waitcnt lgkmcnt(2)
	v_cvt_pk_bf16_f32 v3, v22, v23
	v_ashrrev_i32_e32 v11, 31, v10
	s_waitcnt lgkmcnt(1)
	v_cvt_pk_bf16_f32 v4, v24, v25
	v_lshlrev_b64 v[10:11], 11, v[10:11]
	s_waitcnt lgkmcnt(0)
	v_cvt_pk_bf16_f32 v5, v26, v27
	v_lshl_add_u64 v[6:7], v[8:9], 0, v[10:11]
	global_store_dwordx4 v[6:7], v[2:5], off
	s_waitcnt lgkmcnt(0)

.LBB0_35:
	s_andn2_b64 vcc, exec, s[4:5]
	s_cbranch_vccnz .LBB0_37
	s_and_b32 s4, s35, 0x7fc0
	s_addk_i32 s4, 0xc100
	s_and_b32 s14, s9, 0x3e0
	v_or_b32_e32 v36, s4, v1
	s_lshl_b32 s26, s14, 2
	v_or_b32_e32 v4, 8, v36
	v_mov_b32_e32 v5, v37
	v_or_b32_e32 v10, 16, v36
	v_mov_b32_e32 v11, v37
	v_or_b32_e32 v12, 24, v36
	v_mov_b32_e32 v13, v37
	v_or_b32_e32 v18, 32, v36
	v_mov_b32_e32 v19, v37
	v_or_b32_e32 v20, 40, v36
	v_mov_b32_e32 v21, v37
	v_lshl_add_u64 v[30:31], v[58:59], 0, s[26:27]
	v_lshlrev_b64 v[2:3], 12, v[36:37]
	v_lshlrev_b64 v[4:5], 12, v[4:5]
	v_lshlrev_b64 v[10:11], 12, v[10:11]
	v_lshlrev_b64 v[12:13], 12, v[12:13]
	v_lshlrev_b64 v[18:19], 12, v[18:19]
	v_lshlrev_b64 v[20:21], 12, v[20:21]
	v_lshl_add_u64 v[2:3], v[30:31], 0, v[2:3]
	v_lshl_add_u64 v[6:7], v[30:31], 0, v[4:5]
	v_lshl_add_u64 v[10:11], v[30:31], 0, v[10:11]
	v_lshl_add_u64 v[14:15], v[30:31], 0, v[12:13]
	v_lshl_add_u64 v[18:19], v[30:31], 0, v[18:19]
	v_lshl_add_u64 v[22:23], v[30:31], 0, v[20:21]
	global_load_dwordx4 v[2:5], v[2:3], off nt
	s_nop 0
	global_load_dwordx4 v[6:9], v[6:7], off nt
	s_nop 0
	global_load_dwordx4 v[10:13], v[10:11], off nt
	s_nop 0
	global_load_dwordx4 v[14:17], v[14:15], off nt
	s_nop 0
	global_load_dwordx4 v[18:21], v[18:19], off nt
	s_nop 0
	global_load_dwordx4 v[22:25], v[22:23], off nt
	v_or_b32_e32 v26, 48, v36
	v_mov_b32_e32 v27, v37
	v_lshlrev_b64 v[26:27], 12, v[26:27]
	v_lshl_add_u64 v[26:27], v[30:31], 0, v[26:27]
	v_or_b32_e32 v36, 56, v36
	global_load_dwordx4 v[26:29], v[26:27], off nt
	v_lshlrev_b64 v[32:33], 12, v[36:37]
	v_lshl_add_u64 v[30:31], v[30:31], 0, v[32:33]
	global_load_dwordx4 v[30:33], v[30:31], off nt
	v_add_u32_e32 v36, 0x428, v87
	v_add_u32_e32 v73, 0x840, v87
	v_add_u32_e32 v75, 0x848, v87
	v_add_u32_e32 v76, 0xc60, v87
	v_add_u32_e32 v89, 0xc68, v87
	v_add_u32_e32 v90, 0x1080, v87
	v_add_u32_e32 v91, 0x1088, v87
	v_add_u32_e32 v92, 0x14a0, v87
	v_add_u32_e32 v93, 0x14a8, v87
	v_add_u32_e32 v94, 0x18c0, v87
	v_add_u32_e32 v95, 0x18c8, v87
	v_add_u32_e32 v96, 0x1ce0, v87
	v_add_u32_e32 v97, 0x1ce8, v87
	s_mov_b32 s5, s27
	s_waitcnt vmcnt(7)
	ds_write2_b32 v87, v2, v3 offset1:1
	ds_write2_b32 v87, v4, v5 offset0:2 offset1:3
	s_waitcnt vmcnt(6)
	ds_write2_b32 v88, v6, v7 offset1:1
	ds_write2_b32 v36, v8, v9 offset1:1
	s_waitcnt vmcnt(5)
	ds_write2_b32 v73, v10, v11 offset1:1
	ds_write2_b32 v75, v12, v13 offset1:1
	s_waitcnt vmcnt(4)
	ds_write2_b32 v76, v14, v15 offset1:1
	ds_write2_b32 v89, v16, v17 offset1:1
	s_waitcnt vmcnt(3)
	ds_write2_b32 v90, v18, v19 offset1:1
	ds_write2_b32 v91, v20, v21 offset1:1
	s_waitcnt vmcnt(2)
	ds_write2_b32 v92, v22, v23 offset1:1
	ds_write2_b32 v93, v24, v25 offset1:1
	s_waitcnt vmcnt(1)
	ds_write2_b32 v94, v26, v27 offset1:1
	ds_write2_b32 v95, v28, v29 offset1:1
	s_waitcnt vmcnt(0)
	ds_write2_b32 v96, v30, v31 offset1:1
	ds_write2_b32 v97, v32, v33 offset1:1
	s_waitcnt lgkmcnt(0)
	ds_read2_b32 v[12:13], v80 offset1:33
	ds_read2_b32 v[14:15], v80 offset0:66 offset1:99
	ds_read2_b32 v[16:17], v80 offset0:132 offset1:165
	ds_read2_b32 v[18:19], v80 offset0:198 offset1:231
	ds_read2_b32 v[20:21], v80 offset0:8 offset1:41
	ds_read2_b32 v[22:23], v80 offset0:74 offset1:107
	ds_read2_b32 v[24:25], v80 offset0:140 offset1:173
	ds_read2_b32 v[26:27], v80 offset0:206 offset1:239
	s_waitcnt lgkmcnt(7)
	v_cvt_pk_bf16_f32 v2, v12, v13
	v_or_b32_e32 v10, s14, v1
	ds_read2_b32 v[12:13], v80 offset0:16 offset1:49
	s_waitcnt lgkmcnt(7)
	v_cvt_pk_bf16_f32 v3, v14, v15
	v_lshl_add_u64 v[8:9], s[4:5], 1, v[42:43]
	v_lshlrev_b32_e32 v36, 11, v10
	ds_read2_b32 v[14:15], v80 offset0:82 offset1:115
	s_waitcnt lgkmcnt(7)
	v_cvt_pk_bf16_f32 v4, v16, v17
	ds_read2_b32 v[16:17], v80 offset0:148 offset1:181
	s_waitcnt lgkmcnt(7)
	v_cvt_pk_bf16_f32 v5, v18, v19
	v_lshl_add_u64 v[10:11], v[8:9], 0, v[36:37]
	global_store_dwordx4 v[10:11], v[2:5], off
	v_or_b32_e32 v10, s14, v77
	v_lshlrev_b32_e32 v36, 11, v10
	ds_read2_b32 v[18:19], v80 offset0:214 offset1:247
	s_waitcnt lgkmcnt(7)
	v_cvt_pk_bf16_f32 v2, v20, v21
	ds_read2_b32 v[20:21], v80 offset0:24 offset1:57
	s_waitcnt lgkmcnt(7)
	v_cvt_pk_bf16_f32 v3, v22, v23
	ds_read2_b32 v[22:23], v80 offset0:90 offset1:123
	s_waitcnt lgkmcnt(7)
	v_cvt_pk_bf16_f32 v4, v24, v25
	ds_read2_b32 v[24:25], v80 offset0:156 offset1:189
	s_waitcnt lgkmcnt(7)
	v_cvt_pk_bf16_f32 v5, v26, v27
	v_lshl_add_u64 v[10:11], v[8:9], 0, v[36:37]
	global_store_dwordx4 v[10:11], v[2:5], off
	v_or_b32_e32 v10, s14, v78
	v_lshlrev_b32_e32 v36, 11, v10
	ds_read2_b32 v[26:27], v80 offset0:222 offset1:255
	s_waitcnt lgkmcnt(7)
	v_cvt_pk_bf16_f32 v2, v12, v13
	s_waitcnt lgkmcnt(6)
	v_cvt_pk_bf16_f32 v3, v14, v15
	s_waitcnt lgkmcnt(5)
	v_cvt_pk_bf16_f32 v4, v16, v17
	s_waitcnt lgkmcnt(4)
	v_cvt_pk_bf16_f32 v5, v18, v19
	v_lshl_add_u64 v[10:11], v[8:9], 0, v[36:37]
	global_store_dwordx4 v[10:11], v[2:5], off
	s_nop 0
	s_waitcnt lgkmcnt(3)
	v_cvt_pk_bf16_f32 v2, v20, v21
	s_waitcnt lgkmcnt(2)
	v_cvt_pk_bf16_f32 v3, v22, v23
	s_waitcnt lgkmcnt(1)
	v_cvt_pk_bf16_f32 v4, v24, v25
	v_or_b32_e32 v5, s14, v79
	v_lshlrev_b32_e32 v36, 11, v5
	s_waitcnt lgkmcnt(0)
	v_cvt_pk_bf16_f32 v5, v26, v27
	v_lshl_add_u64 v[6:7], v[8:9], 0, v[36:37]
	global_store_dwordx4 v[6:7], v[2:5], off
	s_waitcnt lgkmcnt(0)

.LBB0_47:
	v_add_u32_e32 v10, 0x18c0, v87
	ds_write2_b32 v10, v6, v7 offset1:1
	v_add_u32_e32 v6, 0x18c8, v87
	ds_write2_b32 v6, v8, v9 offset1:1
	s_waitcnt vmcnt(0)
	v_pk_mul_f32 v[2:3], v[2:3], v[18:19] op_sel_hi:[1,0]
	v_add_u32_e32 v6, 0x1ce0, v87
	ds_write2_b32 v6, v2, v3 offset1:1
	v_pk_mul_f32 v[2:3], v[4:5], v[18:19] op_sel_hi:[1,0]
	v_add_u32_e32 v4, 0x1ce8, v87
	ds_write2_b32 v4, v2, v3 offset1:1
	s_lshl_b32 s4, s14, 5
	s_waitcnt lgkmcnt(0)
	s_addk_i32 s4, 0x600
	s_and_b32 s56, s4, 0x60
	ds_read2_b32 v[12:13], v80 offset1:33
	ds_read2_b32 v[14:15], v80 offset0:66 offset1:99
	ds_read2_b32 v[16:17], v80 offset0:132 offset1:165
	ds_read2_b32 v[18:19], v80 offset0:198 offset1:231
	ds_read2_b32 v[20:21], v80 offset0:8 offset1:41
	ds_read2_b32 v[22:23], v80 offset0:74 offset1:107
	ds_read2_b32 v[24:25], v80 offset0:140 offset1:173
	ds_read2_b32 v[26:27], v80 offset0:206 offset1:239
	s_waitcnt lgkmcnt(7)
	v_cvt_pk_bf16_f32 v2, v12, v13
	s_cmp_lg_u32 s56, 0
	ds_read2_b32 v[12:13], v80 offset0:16 offset1:49
	s_waitcnt lgkmcnt(7)
	v_cvt_pk_bf16_f32 v3, v14, v15
	s_cselect_b64 s[14:15], -1, 0
	s_cmp_eq_u32 s56, 0
	v_mov_b32_e32 v8, v81
	ds_read2_b32 v[14:15], v80 offset0:82 offset1:115
	s_waitcnt lgkmcnt(7)
	v_cvt_pk_bf16_f32 v4, v16, v17
	ds_read2_b32 v[16:17], v80 offset0:148 offset1:181
	s_waitcnt lgkmcnt(7)
	v_cvt_pk_bf16_f32 v5, v18, v19
	s_cbranch_scc1 .LBB0_49
	v_or_b32_e32 v6, s56, v1
	v_subrev_u16_e32 v6, 32, v6
	v_mul_lo_u16_sdwa v7, v6, s48 dst_sel:DWORD dst_unused:UNUSED_PAD src0_sel:BYTE_0 src1_sel:DWORD
	v_lshrrev_b16_e32 v7, 12, v7
	v_mul_lo_u16_e32 v8, 24, v7
	v_sub_u16_e32 v6, v6, v8
	v_add_u16_e32 v6, 8, v6
	v_and_b32_e32 v6, 0xff, v6
	v_lshl_add_u32 v8, v7, 5, v6
	.LBB0_49:
	s_and_b32 s5, 0xffff, s51
	s_and_b32 s4, s4, 0xffff
	s_lshl_b32 s26, s5, 1
	v_lshl_add_u64 v[6:7], v[44:45], 0, s[26:27]
	s_and_b32 s26, s4, 0x1f80
	v_add_lshl_u32 v36, v8, s26, 11
	v_lshl_add_u64 v[8:9], v[6:7], 0, v[36:37]
	global_store_dwordx4 v[8:9], v[2:5], off
	s_andn2_b64 vcc, exec, s[14:15]
	ds_read2_b32 v[18:19], v80 offset0:214 offset1:247
	s_waitcnt lgkmcnt(7)
	v_cvt_pk_bf16_f32 v2, v20, v21
	ds_read2_b32 v[20:21], v80 offset0:24 offset1:57
	s_waitcnt lgkmcnt(7)
	v_cvt_pk_bf16_f32 v3, v22, v23
	ds_read2_b32 v[22:23], v80 offset0:90 offset1:123
	s_waitcnt lgkmcnt(7)
	v_cvt_pk_bf16_f32 v4, v24, v25
	v_cndmask_b32_e64 v5, 0, 1, s[14:15]
	v_cmp_ne_u32_e64 s[4:5], 1, v5
	ds_read2_b32 v[24:25], v80 offset0:156 offset1:189
	s_waitcnt lgkmcnt(7)
	v_cvt_pk_bf16_f32 v5, v26, v27
	v_mov_b32_e32 v8, v84
	s_cbranch_vccnz .LBB0_51
	v_or_b32_e32 v8, s56, v77
	v_subrev_u16_e32 v8, 32, v8
	v_mul_lo_u16_sdwa v9, v8, s48 dst_sel:DWORD dst_unused:UNUSED_PAD src0_sel:BYTE_0 src1_sel:DWORD
	v_lshrrev_b16_e32 v9, 12, v9
	v_mul_lo_u16_e32 v10, 24, v9
	v_sub_u16_e32 v8, v8, v10
	v_add_u16_e32 v8, 8, v8
	v_and_b32_e32 v8, 0xff, v8
	v_lshl_add_u32 v8, v9, 5, v8
	.LBB0_51:
	v_add_lshl_u32 v36, v8, s26, 11
	v_lshl_add_u64 v[8:9], v[6:7], 0, v[36:37]
	global_store_dwordx4 v[8:9], v[2:5], off
	s_and_b64 vcc, exec, s[4:5]
	ds_read2_b32 v[26:27], v80 offset0:222 offset1:255
	s_waitcnt lgkmcnt(7)
	v_cvt_pk_bf16_f32 v2, v12, v13
	s_waitcnt lgkmcnt(6)
	v_cvt_pk_bf16_f32 v3, v14, v15
	s_waitcnt lgkmcnt(5)
	v_cvt_pk_bf16_f32 v4, v16, v17
	s_waitcnt lgkmcnt(4)
	v_cvt_pk_bf16_f32 v5, v18, v19
	v_mov_b32_e32 v8, v85
	s_cbranch_vccnz .LBB0_53
	v_or_b32_e32 v8, s56, v78
	v_subrev_u16_e32 v8, 32, v8
	v_mul_lo_u16_sdwa v9, v8, s48 dst_sel:DWORD dst_unused:UNUSED_PAD src0_sel:BYTE_0 src1_sel:DWORD
	v_lshrrev_b16_e32 v9, 12, v9
	v_mul_lo_u16_e32 v10, 24, v9
	v_sub_u16_e32 v8, v8, v10
	v_add_u16_e32 v8, 8, v8
	v_and_b32_e32 v8, 0xff, v8
	v_lshl_add_u32 v8, v9, 5, v8
	.LBB0_53:
	v_add_lshl_u32 v36, v8, s26, 11
	v_lshl_add_u64 v[8:9], v[6:7], 0, v[36:37]
	global_store_dwordx4 v[8:9], v[2:5], off
	s_and_b64 vcc, exec, s[4:5]
	s_waitcnt lgkmcnt(3)
	v_cvt_pk_bf16_f32 v2, v20, v21
	s_waitcnt lgkmcnt(2)
	v_cvt_pk_bf16_f32 v3, v22, v23
	s_waitcnt lgkmcnt(1)
	v_cvt_pk_bf16_f32 v4, v24, v25
	s_waitcnt lgkmcnt(0)
	v_cvt_pk_bf16_f32 v5, v26, v27
	v_mov_b32_e32 v8, v86
	s_cbranch_vccnz .LBB0_55
	v_or_b32_e32 v8, s56, v79
	v_subrev_u16_e32 v8, 32, v8
	v_mul_lo_u16_sdwa v9, v8, s48 dst_sel:DWORD dst_unused:UNUSED_PAD src0_sel:BYTE_0 src1_sel:DWORD
	v_lshrrev_b16_e32 v9, 12, v9
	v_mul_lo_u16_e32 v10, 24, v9
	v_sub_u16_e32 v8, v8, v10
	v_add_u16_e32 v8, 8, v8
	v_and_b32_e32 v8, 0xff, v8
	v_lshl_add_u32 v8, v9, 5, v8
	.LBB0_55:
	v_add_lshl_u32 v36, v8, s26, 11
	v_lshl_add_u64 v[6:7], v[6:7], 0, v[36:37]
	global_store_dwordx4 v[6:7], v[2:5], off
	s_waitcnt lgkmcnt(0)

.LBB0_66:
	v_add_u32_e32 v10, 0x18c0, v87
	ds_write2_b32 v10, v6, v7 offset1:1
	v_add_u32_e32 v6, 0x18c8, v87
	ds_write2_b32 v6, v8, v9 offset1:1
	s_waitcnt vmcnt(0)
	v_pk_mul_f32 v[2:3], v[2:3], v[18:19] op_sel_hi:[1,0]
	v_add_u32_e32 v6, 0x1ce0, v87
	ds_write2_b32 v6, v2, v3 offset1:1
	v_pk_mul_f32 v[2:3], v[4:5], v[18:19] op_sel_hi:[1,0]
	v_add_u32_e32 v4, 0x1ce8, v87
	ds_write2_b32 v4, v2, v3 offset1:1
	s_waitcnt lgkmcnt(0)
	s_lshl_b32 s56, s14, 5
	s_and_b32 s4, s14, 8
	ds_read2_b32 v[12:13], v80 offset1:33
	ds_read2_b32 v[14:15], v80 offset0:66 offset1:99
	ds_read2_b32 v[16:17], v80 offset0:132 offset1:165
	ds_read2_b32 v[18:19], v80 offset0:198 offset1:231
	ds_read2_b32 v[20:21], v80 offset0:8 offset1:41
	ds_read2_b32 v[22:23], v80 offset0:74 offset1:107
	ds_read2_b32 v[24:25], v80 offset0:140 offset1:173
	ds_read2_b32 v[26:27], v80 offset0:206 offset1:239
	s_waitcnt lgkmcnt(7)
	v_cvt_pk_bf16_f32 v2, v12, v13
	s_cmp_eq_u32 s4, 0
	ds_read2_b32 v[12:13], v80 offset0:16 offset1:49
	s_waitcnt lgkmcnt(7)
	v_cvt_pk_bf16_f32 v3, v14, v15
	s_cselect_b64 s[14:15], -1, 0
	s_cmp_lg_u32 s4, 0
	v_or_b32_e32 v8, s56, v1
	ds_read2_b32 v[14:15], v80 offset0:82 offset1:115
	s_waitcnt lgkmcnt(7)
	v_cvt_pk_bf16_f32 v4, v16, v17
	ds_read2_b32 v[16:17], v80 offset0:148 offset1:181
	s_waitcnt lgkmcnt(7)
	v_cvt_pk_bf16_f32 v5, v18, v19
	s_cbranch_scc1 .LBB0_70
	v_and_b32_e32 v7, 0x67, v8
	v_cmp_lt_u32_e32 vcc, 31, v7
	v_mov_b32_e32 v6, v81
	s_and_saveexec_b64 s[4:5], vcc
	v_subrev_u16_e32 v6, 32, v7
	v_mul_lo_u16_sdwa v7, v6, s48 dst_sel:DWORD dst_unused:UNUSED_PAD src0_sel:BYTE_0 src1_sel:DWORD
	v_lshrrev_b16_e32 v7, 12, v7
	v_mul_lo_u16_e32 v8, 24, v7
	v_sub_u16_e32 v6, v6, v8
	v_add_u16_e32 v6, 8, v6
	v_and_b32_e32 v6, 0xff, v6
	v_lshl_add_u32 v6, v7, 5, v6
	s_or_b64 exec, exec, s[4:5]
	s_and_b32 s4, s56, 0x680
	v_add_u32_e32 v8, s4, v6
	.LBB0_70:
	s_lshl_b32 s26, s51, 1
	v_lshl_add_u64 v[6:7], v[44:45], 0, s[26:27]
	v_lshlrev_b32_e32 v36, 11, v8
	v_lshl_add_u64 v[8:9], v[6:7], 0, v[36:37]
	global_store_dwordx4 v[8:9], v[2:5], off
	s_andn2_b64 vcc, exec, s[14:15]
	ds_read2_b32 v[18:19], v80 offset0:214 offset1:247
	s_waitcnt lgkmcnt(7)
	v_cvt_pk_bf16_f32 v2, v20, v21
	ds_read2_b32 v[20:21], v80 offset0:24 offset1:57
	s_waitcnt lgkmcnt(7)
	v_cvt_pk_bf16_f32 v3, v22, v23
	ds_read2_b32 v[22:23], v80 offset0:90 offset1:123
	s_waitcnt lgkmcnt(7)
	v_cvt_pk_bf16_f32 v4, v24, v25
	v_cndmask_b32_e64 v5, 0, 1, s[14:15]
	v_cmp_ne_u32_e64 s[4:5], 1, v5
	ds_read2_b32 v[24:25], v80 offset0:156 offset1:189
	s_waitcnt lgkmcnt(7)
	v_cvt_pk_bf16_f32 v5, v26, v27
	v_or_b32_e32 v8, s56, v77
	s_cbranch_vccnz .LBB0_74
	v_and_b32_e32 v9, 0x6f, v8
	v_cmp_lt_u32_e32 vcc, 31, v9
	v_mov_b32_e32 v8, v84
	s_and_saveexec_b64 s[14:15], vcc
	v_subrev_u16_e32 v8, 32, v9
	v_mul_lo_u16_sdwa v9, v8, s48 dst_sel:DWORD dst_unused:UNUSED_PAD src0_sel:BYTE_0 src1_sel:DWORD
	v_lshrrev_b16_e32 v9, 12, v9
	v_mul_lo_u16_e32 v10, 24, v9
	v_sub_u16_e32 v8, v8, v10
	v_add_u16_e32 v8, 8, v8
	v_and_b32_e32 v8, 0xff, v8
	v_lshl_add_u32 v8, v9, 5, v8
	s_or_b64 exec, exec, s[14:15]
	s_and_b32 s14, s56, 0x680
	v_add_u32_e32 v8, s14, v8
	.LBB0_74:
	v_lshlrev_b32_e32 v36, 11, v8
	v_lshl_add_u64 v[8:9], v[6:7], 0, v[36:37]
	global_store_dwordx4 v[8:9], v[2:5], off
	s_and_b64 vcc, exec, s[4:5]
	ds_read2_b32 v[26:27], v80 offset0:222 offset1:255
	s_waitcnt lgkmcnt(7)
	v_cvt_pk_bf16_f32 v2, v12, v13
	s_waitcnt lgkmcnt(6)
	v_cvt_pk_bf16_f32 v3, v14, v15
	s_waitcnt lgkmcnt(5)
	v_cvt_pk_bf16_f32 v4, v16, v17
	s_waitcnt lgkmcnt(4)
	v_cvt_pk_bf16_f32 v5, v18, v19
	v_or_b32_e32 v8, s56, v78
	s_cbranch_vccnz .LBB0_78
	v_and_b32_e32 v9, 0x77, v8
	v_cmp_lt_u32_e32 vcc, 31, v9
	v_mov_b32_e32 v8, v85
	s_and_saveexec_b64 s[14:15], vcc
	v_subrev_u16_e32 v8, 32, v9
	v_mul_lo_u16_sdwa v9, v8, s48 dst_sel:DWORD dst_unused:UNUSED_PAD src0_sel:BYTE_0 src1_sel:DWORD
	v_lshrrev_b16_e32 v9, 12, v9
	v_mul_lo_u16_e32 v10, 24, v9
	v_sub_u16_e32 v8, v8, v10
	v_add_u16_e32 v8, 8, v8
	v_and_b32_e32 v8, 0xff, v8
	v_lshl_add_u32 v8, v9, 5, v8
	s_or_b64 exec, exec, s[14:15]
	s_and_b32 s14, s56, 0x680
	v_add_u32_e32 v8, s14, v8
	.LBB0_78:
	v_lshlrev_b32_e32 v36, 11, v8
	v_lshl_add_u64 v[8:9], v[6:7], 0, v[36:37]
	global_store_dwordx4 v[8:9], v[2:5], off
	s_and_b64 vcc, exec, s[4:5]
	s_waitcnt lgkmcnt(3)
	v_cvt_pk_bf16_f32 v2, v20, v21
	s_waitcnt lgkmcnt(2)
	v_cvt_pk_bf16_f32 v3, v22, v23
	s_waitcnt lgkmcnt(1)
	v_cvt_pk_bf16_f32 v4, v24, v25
	s_waitcnt lgkmcnt(0)
	v_cvt_pk_bf16_f32 v5, v26, v27
	v_or_b32_e32 v8, s56, v79
	s_cbranch_vccnz .LBB0_82
	v_and_b32_e32 v9, 0x7f, v8
	v_cmp_lt_u32_e32 vcc, 31, v9
	v_mov_b32_e32 v8, v86
	s_and_saveexec_b64 s[4:5], vcc
	v_subrev_u16_e32 v8, 32, v9
	v_mul_lo_u16_sdwa v9, v8, s48 dst_sel:DWORD dst_unused:UNUSED_PAD src0_sel:BYTE_0 src1_sel:DWORD
	v_lshrrev_b16_e32 v9, 12, v9
	v_mul_lo_u16_e32 v10, 24, v9
	v_sub_u16_e32 v8, v8, v10
	v_add_u16_e32 v8, 8, v8
	v_and_b32_e32 v8, 0xff, v8
	v_lshl_add_u32 v8, v9, 5, v8
	s_or_b64 exec, exec, s[4:5]
	s_and_b32 s4, s56, 0x680
	v_add_u32_e32 v8, s4, v8
	.LBB0_82:
	v_lshlrev_b32_e32 v36, 11, v8
	v_lshl_add_u64 v[6:7], v[6:7], 0, v[36:37]
	global_store_dwordx4 v[6:7], v[2:5], off
	s_waitcnt lgkmcnt(0)

.LBB0_84:
	s_andn2_b64 vcc, exec, s[4:5]
	s_cbranch_vccnz .LBB0_86
	s_and_b32 s4, s35, 0x3fc0
	s_addk_i32 s4, 0xde00
	s_and_b32 s14, s9, 0x3e0
	v_or_b32_e32 v36, s4, v1
	s_lshl_b32 s26, s14, 2
	v_or_b32_e32 v4, 8, v36
	v_mov_b32_e32 v5, v37
	v_or_b32_e32 v10, 16, v36
	v_mov_b32_e32 v11, v37
	v_or_b32_e32 v12, 24, v36
	v_mov_b32_e32 v13, v37
	v_or_b32_e32 v18, 32, v36
	v_mov_b32_e32 v19, v37
	v_or_b32_e32 v20, 40, v36
	v_mov_b32_e32 v21, v37
	v_lshl_add_u64 v[30:31], v[64:65], 0, s[26:27]
	v_lshlrev_b64 v[2:3], 12, v[36:37]
	v_lshlrev_b64 v[4:5], 12, v[4:5]
	v_lshlrev_b64 v[10:11], 12, v[10:11]
	v_lshlrev_b64 v[12:13], 12, v[12:13]
	v_lshlrev_b64 v[18:19], 12, v[18:19]
	v_lshlrev_b64 v[20:21], 12, v[20:21]
	v_lshl_add_u64 v[2:3], v[30:31], 0, v[2:3]
	v_lshl_add_u64 v[6:7], v[30:31], 0, v[4:5]
	v_lshl_add_u64 v[10:11], v[30:31], 0, v[10:11]
	v_lshl_add_u64 v[14:15], v[30:31], 0, v[12:13]
	v_lshl_add_u64 v[18:19], v[30:31], 0, v[18:19]
	v_lshl_add_u64 v[22:23], v[30:31], 0, v[20:21]
	global_load_dwordx4 v[2:5], v[2:3], off nt
	s_nop 0
	global_load_dwordx4 v[6:9], v[6:7], off nt
	s_nop 0
	global_load_dwordx4 v[10:13], v[10:11], off nt
	s_nop 0
	global_load_dwordx4 v[14:17], v[14:15], off nt
	s_nop 0
	global_load_dwordx4 v[18:21], v[18:19], off nt
	s_nop 0
	global_load_dwordx4 v[22:25], v[22:23], off nt
	v_or_b32_e32 v26, 48, v36
	v_mov_b32_e32 v27, v37
	v_lshlrev_b64 v[26:27], 12, v[26:27]
	v_lshl_add_u64 v[26:27], v[30:31], 0, v[26:27]
	v_or_b32_e32 v36, 56, v36
	global_load_dwordx4 v[26:29], v[26:27], off nt
	v_lshlrev_b64 v[32:33], 12, v[36:37]
	v_lshl_add_u64 v[30:31], v[30:31], 0, v[32:33]
	global_load_dwordx4 v[30:33], v[30:31], off nt
	v_add_u32_e32 v36, 0x428, v87
	v_add_u32_e32 v73, 0x840, v87
	v_add_u32_e32 v75, 0x848, v87
	v_add_u32_e32 v76, 0xc60, v87
	v_add_u32_e32 v89, 0xc68, v87
	v_add_u32_e32 v90, 0x1080, v87
	v_add_u32_e32 v91, 0x1088, v87
	v_add_u32_e32 v92, 0x14a0, v87
	v_add_u32_e32 v93, 0x14a8, v87
	v_add_u32_e32 v94, 0x18c0, v87
	v_add_u32_e32 v95, 0x18c8, v87
	v_add_u32_e32 v96, 0x1ce0, v87
	v_add_u32_e32 v97, 0x1ce8, v87
	s_mov_b32 s5, s27
	s_waitcnt vmcnt(7)
	ds_write2_b32 v87, v2, v3 offset1:1
	ds_write2_b32 v87, v4, v5 offset0:2 offset1:3
	s_waitcnt vmcnt(6)
	ds_write2_b32 v88, v6, v7 offset1:1
	ds_write2_b32 v36, v8, v9 offset1:1
	s_waitcnt vmcnt(5)
	ds_write2_b32 v73, v10, v11 offset1:1
	ds_write2_b32 v75, v12, v13 offset1:1
	s_waitcnt vmcnt(4)
	ds_write2_b32 v76, v14, v15 offset1:1
	ds_write2_b32 v89, v16, v17 offset1:1
	s_waitcnt vmcnt(3)
	ds_write2_b32 v90, v18, v19 offset1:1
	ds_write2_b32 v91, v20, v21 offset1:1
	s_waitcnt vmcnt(2)
	ds_write2_b32 v92, v22, v23 offset1:1
	ds_write2_b32 v93, v24, v25 offset1:1
	s_waitcnt vmcnt(1)
	ds_write2_b32 v94, v26, v27 offset1:1
	ds_write2_b32 v95, v28, v29 offset1:1
	s_waitcnt vmcnt(0)
	ds_write2_b32 v96, v30, v31 offset1:1
	ds_write2_b32 v97, v32, v33 offset1:1
	s_waitcnt lgkmcnt(0)
	v_or_b32_e32 v10, s14, v1
	v_mul_u32_u24_e32 v10, 0xb00, v10
	ds_read2_b32 v[12:13], v80 offset1:33
	ds_read2_b32 v[14:15], v80 offset0:66 offset1:99
	ds_read2_b32 v[16:17], v80 offset0:132 offset1:165
	ds_read2_b32 v[18:19], v80 offset0:198 offset1:231
	ds_read2_b32 v[20:21], v80 offset0:8 offset1:41
	ds_read2_b32 v[22:23], v80 offset0:74 offset1:107
	ds_read2_b32 v[24:25], v80 offset0:140 offset1:173
	ds_read2_b32 v[26:27], v80 offset0:206 offset1:239
	s_waitcnt lgkmcnt(7)
	v_cvt_pk_bf16_f32 v2, v12, v13
	v_lshl_add_u64 v[8:9], s[4:5], 1, v[46:47]
	v_lshlrev_b32_e32 v36, 1, v10
	ds_read2_b32 v[12:13], v80 offset0:16 offset1:49
	s_waitcnt lgkmcnt(7)
	v_cvt_pk_bf16_f32 v3, v14, v15
	v_lshl_add_u64 v[10:11], v[8:9], 0, v[36:37]
	ds_read2_b32 v[14:15], v80 offset0:82 offset1:115
	s_waitcnt lgkmcnt(7)
	v_cvt_pk_bf16_f32 v4, v16, v17
	ds_read2_b32 v[16:17], v80 offset0:148 offset1:181
	s_waitcnt lgkmcnt(7)
	v_cvt_pk_bf16_f32 v5, v18, v19
	global_store_dwordx4 v[10:11], v[2:5], off
	v_or_b32_e32 v10, s14, v77
	v_mul_u32_u24_e32 v10, 0xb00, v10
	ds_read2_b32 v[18:19], v80 offset0:214 offset1:247
	s_waitcnt lgkmcnt(7)
	v_cvt_pk_bf16_f32 v2, v20, v21
	v_lshlrev_b32_e32 v36, 1, v10
	ds_read2_b32 v[20:21], v80 offset0:24 offset1:57
	s_waitcnt lgkmcnt(7)
	v_cvt_pk_bf16_f32 v3, v22, v23
	v_lshl_add_u64 v[10:11], v[8:9], 0, v[36:37]
	ds_read2_b32 v[22:23], v80 offset0:90 offset1:123
	s_waitcnt lgkmcnt(7)
	v_cvt_pk_bf16_f32 v4, v24, v25
	ds_read2_b32 v[24:25], v80 offset0:156 offset1:189
	s_waitcnt lgkmcnt(7)
	v_cvt_pk_bf16_f32 v5, v26, v27
	global_store_dwordx4 v[10:11], v[2:5], off
	v_or_b32_e32 v10, s14, v78
	ds_read2_b32 v[26:27], v80 offset0:222 offset1:255
	s_waitcnt lgkmcnt(7)
	v_cvt_pk_bf16_f32 v2, v12, v13
	v_mul_u32_u24_e32 v10, 0xb00, v10
	s_waitcnt lgkmcnt(6)
	v_cvt_pk_bf16_f32 v3, v14, v15
	v_lshlrev_b32_e32 v36, 1, v10
	s_waitcnt lgkmcnt(5)
	v_cvt_pk_bf16_f32 v4, v16, v17
	s_waitcnt lgkmcnt(4)
	v_cvt_pk_bf16_f32 v5, v18, v19
	v_lshl_add_u64 v[10:11], v[8:9], 0, v[36:37]
	global_store_dwordx4 v[10:11], v[2:5], off
	s_nop 0
	s_waitcnt lgkmcnt(3)
	v_cvt_pk_bf16_f32 v2, v20, v21
	s_waitcnt lgkmcnt(2)
	v_cvt_pk_bf16_f32 v3, v22, v23
	s_waitcnt lgkmcnt(1)
	v_cvt_pk_bf16_f32 v4, v24, v25
	v_or_b32_e32 v5, s14, v79
	v_mul_u32_u24_e32 v5, 0xb00, v5
	v_lshlrev_b32_e32 v36, 1, v5
	s_waitcnt lgkmcnt(0)
	v_cvt_pk_bf16_f32 v5, v26, v27
	v_lshl_add_u64 v[6:7], v[8:9], 0, v[36:37]
	global_store_dwordx4 v[6:7], v[2:5], off
	s_waitcnt lgkmcnt(0)

.LBB0_96:
	s_lshl_b32 s4, s15, 5
	s_and_b32 s5, 0xffff, s15
	s_add_i32 s15, s4, 0xf500
	s_cmpk_lt_u32 s5, 0x58
	s_cselect_b32 s4, s4, s15
	s_sext_i32_i16 s5, s4
	s_cselect_b32 s15, 0, 0x80
	s_bfe_u32 s5, s5, 0x70018
	v_add_u32_e32 v10, 0x18c0, v87
	s_add_i32 s5, s4, s5
	ds_write2_b32 v10, v6, v7 offset1:1
	v_add_u32_e32 v6, 0x18c8, v87
	s_sext_i32_i16 s26, s5
	s_and_b32 s5, s5, 0xff80
	ds_write2_b32 v6, v8, v9 offset1:1
	s_waitcnt vmcnt(0)
	v_pk_mul_f32 v[2:3], v[2:3], v[18:19] op_sel_hi:[1,0]
	v_add_u32_e32 v6, 0x1ce0, v87
	s_sub_i32 s4, s4, s5
	ds_write2_b32 v6, v2, v3 offset1:1
	v_pk_mul_f32 v[2:3], v[4:5], v[18:19] op_sel_hi:[1,0]
	v_add_u32_e32 v4, 0x1ce8, v87
	s_lshl_b32 s26, s26, 1
	s_sext_i32_i16 s4, s4
	ds_write2_b32 v4, v2, v3 offset1:1
	s_and_b32 s26, s26, 0xffffff00
	s_add_i32 s4, s15, s4
	s_waitcnt lgkmcnt(0)
	s_add_i32 s4, s4, s26
	s_and_b32 s5, 0xffff, s14
	v_add_u32_e32 v10, s4, v1
	ds_read2_b32 v[12:13], v80 offset1:33
	ds_read2_b32 v[14:15], v80 offset0:66 offset1:99
	ds_read2_b32 v[16:17], v80 offset0:132 offset1:165
	ds_read2_b32 v[18:19], v80 offset0:198 offset1:231
	ds_read2_b32 v[20:21], v80 offset0:8 offset1:41
	ds_read2_b32 v[22:23], v80 offset0:74 offset1:107
	ds_read2_b32 v[24:25], v80 offset0:140 offset1:173
	ds_read2_b32 v[26:27], v80 offset0:206 offset1:239
	s_waitcnt lgkmcnt(7)
	v_cvt_pk_bf16_f32 v2, v12, v13
	s_lshl_b32 s26, s5, 1
	v_ashrrev_i32_e32 v11, 31, v10
	ds_read2_b32 v[12:13], v80 offset0:16 offset1:49
	s_waitcnt lgkmcnt(7)
	v_cvt_pk_bf16_f32 v3, v14, v15
	v_lshl_add_u64 v[8:9], v[48:49], 0, s[26:27]
	v_lshlrev_b64 v[10:11], 11, v[10:11]
	ds_read2_b32 v[14:15], v80 offset0:82 offset1:115
	s_waitcnt lgkmcnt(7)
	v_cvt_pk_bf16_f32 v4, v16, v17
	ds_read2_b32 v[16:17], v80 offset0:148 offset1:181
	s_waitcnt lgkmcnt(7)
	v_cvt_pk_bf16_f32 v5, v18, v19
	v_lshl_add_u64 v[10:11], v[8:9], 0, v[10:11]
	global_store_dwordx4 v[10:11], v[2:5], off
	s_nop 0
	ds_read2_b32 v[18:19], v80 offset0:214 offset1:247
	s_waitcnt lgkmcnt(7)
	v_cvt_pk_bf16_f32 v2, v20, v21
	ds_read2_b32 v[20:21], v80 offset0:24 offset1:57
	s_waitcnt lgkmcnt(7)
	v_cvt_pk_bf16_f32 v3, v22, v23
	ds_read2_b32 v[22:23], v80 offset0:90 offset1:123
	s_waitcnt lgkmcnt(7)
	v_cvt_pk_bf16_f32 v4, v24, v25
	ds_read2_b32 v[24:25], v80 offset0:156 offset1:189
	s_waitcnt lgkmcnt(7)
	v_cvt_pk_bf16_f32 v5, v26, v27
	v_add_u32_e32 v6, s4, v77
	v_ashrrev_i32_e32 v7, 31, v6
	v_lshlrev_b64 v[6:7], 11, v[6:7]
	v_lshl_add_u64 v[6:7], v[8:9], 0, v[6:7]
	global_store_dwordx4 v[6:7], v[2:5], off
	s_nop 0
	ds_read2_b32 v[26:27], v80 offset0:222 offset1:255
	s_waitcnt lgkmcnt(7)
	v_cvt_pk_bf16_f32 v2, v12, v13
	s_waitcnt lgkmcnt(6)
	v_cvt_pk_bf16_f32 v3, v14, v15
	s_waitcnt lgkmcnt(5)
	v_cvt_pk_bf16_f32 v4, v16, v17
	s_waitcnt lgkmcnt(4)
	v_cvt_pk_bf16_f32 v5, v18, v19
	v_add_u32_e32 v6, s4, v78
	v_ashrrev_i32_e32 v7, 31, v6
	v_lshlrev_b64 v[6:7], 11, v[6:7]
	v_lshl_add_u64 v[6:7], v[8:9], 0, v[6:7]
	global_store_dwordx4 v[6:7], v[2:5], off
	s_nop 0
	s_waitcnt lgkmcnt(3)
	v_cvt_pk_bf16_f32 v2, v20, v21
	v_add_u32_e32 v10, s4, v79
	s_waitcnt lgkmcnt(2)
	v_cvt_pk_bf16_f32 v3, v22, v23
	v_ashrrev_i32_e32 v11, 31, v10
	s_waitcnt lgkmcnt(1)
	v_cvt_pk_bf16_f32 v4, v24, v25
	v_lshlrev_b64 v[10:11], 11, v[10:11]
	s_waitcnt lgkmcnt(0)
	v_cvt_pk_bf16_f32 v5, v26, v27
	v_lshl_add_u64 v[6:7], v[8:9], 0, v[10:11]
	global_store_dwordx4 v[6:7], v[2:5], off
	s_waitcnt lgkmcnt(0)

.LBB0_98:
	s_andn2_b64 vcc, exec, s[4:5]
	s_cbranch_vccnz .LBB0_100
	s_and_b32 s4, s35, 0xfc0
	s_addk_i32 s4, 0xf800
	s_and_b32 s14, s9, 0x3e0
	v_or_b32_e32 v36, s4, v1
	s_lshl_b32 s26, s14, 2
	v_or_b32_e32 v4, 8, v36
	v_mov_b32_e32 v5, v37
	v_or_b32_e32 v10, 16, v36
	v_mov_b32_e32 v11, v37
	v_or_b32_e32 v12, 24, v36
	v_mov_b32_e32 v13, v37
	v_or_b32_e32 v18, 32, v36
	v_mov_b32_e32 v19, v37
	v_or_b32_e32 v20, 40, v36
	v_mov_b32_e32 v21, v37
	v_lshl_add_u64 v[30:31], v[68:69], 0, s[26:27]
	v_lshlrev_b64 v[2:3], 12, v[36:37]
	v_lshlrev_b64 v[4:5], 12, v[4:5]
	v_lshlrev_b64 v[10:11], 12, v[10:11]
	v_lshlrev_b64 v[12:13], 12, v[12:13]
	v_lshlrev_b64 v[18:19], 12, v[18:19]
	v_lshlrev_b64 v[20:21], 12, v[20:21]
	v_lshl_add_u64 v[2:3], v[30:31], 0, v[2:3]
	v_lshl_add_u64 v[6:7], v[30:31], 0, v[4:5]
	v_lshl_add_u64 v[10:11], v[30:31], 0, v[10:11]
	v_lshl_add_u64 v[14:15], v[30:31], 0, v[12:13]
	v_lshl_add_u64 v[18:19], v[30:31], 0, v[18:19]
	v_lshl_add_u64 v[22:23], v[30:31], 0, v[20:21]
	global_load_dwordx4 v[2:5], v[2:3], off nt
	s_nop 0
	global_load_dwordx4 v[6:9], v[6:7], off nt
	s_nop 0
	global_load_dwordx4 v[10:13], v[10:11], off nt
	s_nop 0
	global_load_dwordx4 v[14:17], v[14:15], off nt
	s_nop 0
	global_load_dwordx4 v[18:21], v[18:19], off nt
	s_nop 0
	global_load_dwordx4 v[22:25], v[22:23], off nt
	v_or_b32_e32 v26, 48, v36
	v_mov_b32_e32 v27, v37
	v_lshlrev_b64 v[26:27], 12, v[26:27]
	v_lshl_add_u64 v[26:27], v[30:31], 0, v[26:27]
	v_or_b32_e32 v36, 56, v36
	global_load_dwordx4 v[26:29], v[26:27], off nt
	v_lshlrev_b64 v[32:33], 12, v[36:37]
	v_lshl_add_u64 v[30:31], v[30:31], 0, v[32:33]
	global_load_dwordx4 v[30:33], v[30:31], off nt
	v_add_u32_e32 v36, 0x428, v87
	v_add_u32_e32 v73, 0x840, v87
	v_add_u32_e32 v75, 0x848, v87
	v_add_u32_e32 v76, 0xc60, v87
	v_add_u32_e32 v89, 0xc68, v87
	v_add_u32_e32 v90, 0x1080, v87
	v_add_u32_e32 v91, 0x1088, v87
	v_add_u32_e32 v92, 0x14a0, v87
	v_add_u32_e32 v93, 0x14a8, v87
	v_add_u32_e32 v94, 0x18c0, v87
	v_add_u32_e32 v95, 0x18c8, v87
	v_add_u32_e32 v96, 0x1ce0, v87
	v_add_u32_e32 v97, 0x1ce8, v87
	s_mov_b32 s5, s27
	s_waitcnt vmcnt(7)
	ds_write2_b32 v87, v2, v3 offset1:1
	ds_write2_b32 v87, v4, v5 offset0:2 offset1:3
	s_waitcnt vmcnt(6)
	ds_write2_b32 v88, v6, v7 offset1:1
	ds_write2_b32 v36, v8, v9 offset1:1
	s_waitcnt vmcnt(5)
	ds_write2_b32 v73, v10, v11 offset1:1
	ds_write2_b32 v75, v12, v13 offset1:1
	s_waitcnt vmcnt(4)
	ds_write2_b32 v76, v14, v15 offset1:1
	ds_write2_b32 v89, v16, v17 offset1:1
	s_waitcnt vmcnt(3)
	ds_write2_b32 v90, v18, v19 offset1:1
	ds_write2_b32 v91, v20, v21 offset1:1
	s_waitcnt vmcnt(2)
	ds_write2_b32 v92, v22, v23 offset1:1
	ds_write2_b32 v93, v24, v25 offset1:1
	s_waitcnt vmcnt(1)
	ds_write2_b32 v94, v26, v27 offset1:1
	ds_write2_b32 v95, v28, v29 offset1:1
	s_waitcnt vmcnt(0)
	ds_write2_b32 v96, v30, v31 offset1:1
	ds_write2_b32 v97, v32, v33 offset1:1
	s_waitcnt lgkmcnt(0)
	ds_read2_b32 v[12:13], v80 offset1:33
	ds_read2_b32 v[14:15], v80 offset0:66 offset1:99
	ds_read2_b32 v[16:17], v80 offset0:132 offset1:165
	ds_read2_b32 v[18:19], v80 offset0:198 offset1:231
	ds_read2_b32 v[20:21], v80 offset0:8 offset1:41
	ds_read2_b32 v[22:23], v80 offset0:74 offset1:107
	ds_read2_b32 v[24:25], v80 offset0:140 offset1:173
	ds_read2_b32 v[26:27], v80 offset0:206 offset1:239
	s_waitcnt lgkmcnt(7)
	v_cvt_pk_bf16_f32 v2, v12, v13
	v_or_b32_e32 v10, s14, v1
	ds_read2_b32 v[12:13], v80 offset0:16 offset1:49
	s_waitcnt lgkmcnt(7)
	v_cvt_pk_bf16_f32 v3, v14, v15
	v_lshl_add_u64 v[8:9], s[4:5], 1, v[50:51]
	v_lshlrev_b32_e32 v36, 11, v10
	ds_read2_b32 v[14:15], v80 offset0:82 offset1:115
	s_waitcnt lgkmcnt(7)
	v_cvt_pk_bf16_f32 v4, v16, v17
	ds_read2_b32 v[16:17], v80 offset0:148 offset1:181
	s_waitcnt lgkmcnt(7)
	v_cvt_pk_bf16_f32 v5, v18, v19
	v_lshl_add_u64 v[10:11], v[8:9], 0, v[36:37]
	global_store_dwordx4 v[10:11], v[2:5], off
	v_or_b32_e32 v10, s14, v77
	v_lshlrev_b32_e32 v36, 11, v10
	ds_read2_b32 v[18:19], v80 offset0:214 offset1:247
	s_waitcnt lgkmcnt(7)
	v_cvt_pk_bf16_f32 v2, v20, v21
	ds_read2_b32 v[20:21], v80 offset0:24 offset1:57
	s_waitcnt lgkmcnt(7)
	v_cvt_pk_bf16_f32 v3, v22, v23
	ds_read2_b32 v[22:23], v80 offset0:90 offset1:123
	s_waitcnt lgkmcnt(7)
	v_cvt_pk_bf16_f32 v4, v24, v25
	ds_read2_b32 v[24:25], v80 offset0:156 offset1:189
	s_waitcnt lgkmcnt(7)
	v_cvt_pk_bf16_f32 v5, v26, v27
	v_lshl_add_u64 v[10:11], v[8:9], 0, v[36:37]
	global_store_dwordx4 v[10:11], v[2:5], off
	v_or_b32_e32 v10, s14, v78
	v_lshlrev_b32_e32 v36, 11, v10
	ds_read2_b32 v[26:27], v80 offset0:222 offset1:255
	s_waitcnt lgkmcnt(7)
	v_cvt_pk_bf16_f32 v2, v12, v13
	s_waitcnt lgkmcnt(6)
	v_cvt_pk_bf16_f32 v3, v14, v15
	s_waitcnt lgkmcnt(5)
	v_cvt_pk_bf16_f32 v4, v16, v17
	s_waitcnt lgkmcnt(4)
	v_cvt_pk_bf16_f32 v5, v18, v19
	v_lshl_add_u64 v[10:11], v[8:9], 0, v[36:37]
	global_store_dwordx4 v[10:11], v[2:5], off
	s_nop 0
	s_waitcnt lgkmcnt(3)
	v_cvt_pk_bf16_f32 v2, v20, v21
	s_waitcnt lgkmcnt(2)
	v_cvt_pk_bf16_f32 v3, v22, v23
	s_waitcnt lgkmcnt(1)
	v_cvt_pk_bf16_f32 v4, v24, v25
	v_or_b32_e32 v5, s14, v79
	v_lshlrev_b32_e32 v36, 11, v5
	s_waitcnt lgkmcnt(0)
	v_cvt_pk_bf16_f32 v5, v26, v27
	v_lshl_add_u64 v[6:7], v[8:9], 0, v[36:37]
	global_store_dwordx4 v[6:7], v[2:5], off
	s_waitcnt lgkmcnt(0)

.LBB0_101:
	s_andn2_b64 vcc, exec, s[4:5]
	s_cbranch_vccnz .LBB0_10
	s_ashr_i32 s4, s50, 31
	s_lshr_b32 s4, s4, 26
	s_add_i32 s5, s50, s4
	s_lshl_b32 s4, s5, 5
	s_and_b32 s14, s5, 0xffffffc0
	s_and_b32 s4, s4, 0xfffff800
	v_or_b32_e32 v30, s14, v1
	s_sub_i32 s4, s9, s4
	v_or_b32_e32 v4, 8, v30
	v_or_b32_e32 v10, 16, v30
	v_or_b32_e32 v12, 24, v30
	v_or_b32_e32 v18, 32, v30
	v_or_b32_e32 v20, 40, v30
	s_ashr_i32 s5, s4, 31
	v_ashrrev_i32_e32 v31, 31, v30
	v_ashrrev_i32_e32 v5, 31, v4
	v_ashrrev_i32_e32 v11, 31, v10
	v_ashrrev_i32_e32 v13, 31, v12
	v_ashrrev_i32_e32 v19, 31, v18
	v_ashrrev_i32_e32 v21, 31, v20
	v_lshl_add_u64 v[32:33], s[4:5], 2, v[70:71]
	v_lshlrev_b64 v[2:3], 13, v[30:31]
	v_lshlrev_b64 v[4:5], 13, v[4:5]
	v_lshlrev_b64 v[10:11], 13, v[10:11]
	v_lshlrev_b64 v[12:13], 13, v[12:13]
	v_lshlrev_b64 v[18:19], 13, v[18:19]
	v_lshlrev_b64 v[20:21], 13, v[20:21]
	v_lshl_add_u64 v[2:3], v[32:33], 0, v[2:3]
	v_lshl_add_u64 v[6:7], v[32:33], 0, v[4:5]
	v_lshl_add_u64 v[10:11], v[32:33], 0, v[10:11]
	v_lshl_add_u64 v[14:15], v[32:33], 0, v[12:13]
	v_lshl_add_u64 v[18:19], v[32:33], 0, v[18:19]
	v_lshl_add_u64 v[22:23], v[32:33], 0, v[20:21]
	global_load_dwordx4 v[2:5], v[2:3], off nt
	s_nop 0
	global_load_dwordx4 v[6:9], v[6:7], off nt
	s_nop 0
	global_load_dwordx4 v[10:13], v[10:11], off nt
	s_nop 0
	global_load_dwordx4 v[14:17], v[14:15], off nt
	s_nop 0
	global_load_dwordx4 v[18:21], v[18:19], off nt
	s_nop 0
	global_load_dwordx4 v[22:25], v[22:23], off nt
	v_or_b32_e32 v26, 48, v30
	v_ashrrev_i32_e32 v27, 31, v26
	v_lshlrev_b64 v[26:27], 13, v[26:27]
	v_or_b32_e32 v30, 56, v30
	v_lshl_add_u64 v[26:27], v[32:33], 0, v[26:27]
	v_ashrrev_i32_e32 v31, 31, v30
	global_load_dwordx4 v[26:29], v[26:27], off nt
	v_lshlrev_b64 v[30:31], 13, v[30:31]
	v_lshl_add_u64 v[30:31], v[32:33], 0, v[30:31]
	global_load_dwordx4 v[30:33], v[30:31], off nt
	v_add_u32_e32 v36, 0x428, v87
	v_add_u32_e32 v73, 0x840, v87
	v_add_u32_e32 v75, 0x848, v87
	v_add_u32_e32 v76, 0xc60, v87
	v_add_u32_e32 v89, 0xc68, v87
	v_add_u32_e32 v90, 0x1080, v87
	v_add_u32_e32 v91, 0x1088, v87
	v_add_u32_e32 v92, 0x14a0, v87
	v_add_u32_e32 v93, 0x14a8, v87
	v_add_u32_e32 v94, 0x18c0, v87
	v_add_u32_e32 v95, 0x18c8, v87
	v_add_u32_e32 v96, 0x1ce0, v87
	v_add_u32_e32 v97, 0x1ce8, v87
	s_ashr_i32 s15, s14, 31
	s_waitcnt vmcnt(7)
	ds_write2_b32 v87, v2, v3 offset1:1
	ds_write2_b32 v87, v4, v5 offset0:2 offset1:3
	s_waitcnt vmcnt(6)
	ds_write2_b32 v88, v6, v7 offset1:1
	ds_write2_b32 v36, v8, v9 offset1:1
	s_waitcnt vmcnt(5)
	ds_write2_b32 v73, v10, v11 offset1:1
	ds_write2_b32 v75, v12, v13 offset1:1
	s_waitcnt vmcnt(4)
	ds_write2_b32 v76, v14, v15 offset1:1
	ds_write2_b32 v89, v16, v17 offset1:1
	s_waitcnt vmcnt(3)
	ds_write2_b32 v90, v18, v19 offset1:1
	ds_write2_b32 v91, v20, v21 offset1:1
	s_waitcnt vmcnt(2)
	ds_write2_b32 v92, v22, v23 offset1:1
	ds_write2_b32 v93, v24, v25 offset1:1
	s_waitcnt vmcnt(1)
	ds_write2_b32 v94, v26, v27 offset1:1
	ds_write2_b32 v95, v28, v29 offset1:1
	s_waitcnt vmcnt(0)
	ds_write2_b32 v96, v30, v31 offset1:1
	ds_write2_b32 v97, v32, v33 offset1:1
	s_waitcnt lgkmcnt(0)
	v_add_u32_e32 v10, s4, v1
	v_ashrrev_i32_e32 v11, 31, v10
	ds_read2_b32 v[14:15], v80 offset1:33
	ds_read2_b32 v[16:17], v80 offset0:66 offset1:99
	ds_read2_b32 v[18:19], v80 offset0:132 offset1:165
	ds_read2_b32 v[20:21], v80 offset0:198 offset1:231
	ds_read2_b32 v[22:23], v80 offset0:8 offset1:41
	ds_read2_b32 v[24:25], v80 offset0:74 offset1:107
	ds_read2_b32 v[26:27], v80 offset0:140 offset1:173
	ds_read2_b32 v[28:29], v80 offset0:206 offset1:239
	s_waitcnt lgkmcnt(7)
	v_cvt_pk_bf16_f32 v2, v14, v15
	v_lshl_add_u64 v[8:9], s[14:15], 1, v[52:53]
	v_lshlrev_b64 v[12:13], 11, v[10:11]
	ds_read2_b32 v[14:15], v80 offset0:16 offset1:49
	s_waitcnt lgkmcnt(7)
	v_cvt_pk_bf16_f32 v3, v16, v17
	v_lshl_add_u64 v[12:13], v[8:9], 0, v[12:13]
	ds_read2_b32 v[16:17], v80 offset0:82 offset1:115
	s_waitcnt lgkmcnt(7)
	v_cvt_pk_bf16_f32 v4, v18, v19
	ds_read2_b32 v[18:19], v80 offset0:148 offset1:181
	s_waitcnt lgkmcnt(7)
	v_cvt_pk_bf16_f32 v5, v20, v21
	global_store_dwordx4 v[12:13], v[2:5], off
	v_add_u32_e32 v12, 8, v10
	v_ashrrev_i32_e32 v13, 31, v12
	ds_read2_b32 v[20:21], v80 offset0:214 offset1:247
	s_waitcnt lgkmcnt(7)
	v_cvt_pk_bf16_f32 v2, v22, v23
	v_lshlrev_b64 v[12:13], 11, v[12:13]
	ds_read2_b32 v[22:23], v80 offset0:24 offset1:57
	s_waitcnt lgkmcnt(7)
	v_cvt_pk_bf16_f32 v3, v24, v25
	v_lshl_add_u64 v[12:13], v[8:9], 0, v[12:13]
	ds_read2_b32 v[24:25], v80 offset0:90 offset1:123
	s_waitcnt lgkmcnt(7)
	v_cvt_pk_bf16_f32 v4, v26, v27
	ds_read2_b32 v[26:27], v80 offset0:156 offset1:189
	s_waitcnt lgkmcnt(7)
	v_cvt_pk_bf16_f32 v5, v28, v29
	global_store_dwordx4 v[12:13], v[2:5], off
	v_add_u32_e32 v12, 16, v10
	ds_read2_b32 v[28:29], v80 offset0:222 offset1:255
	s_waitcnt lgkmcnt(7)
	v_cvt_pk_bf16_f32 v2, v14, v15
	v_ashrrev_i32_e32 v13, 31, v12
	s_waitcnt lgkmcnt(6)
	v_cvt_pk_bf16_f32 v3, v16, v17
	v_lshlrev_b64 v[12:13], 11, v[12:13]
	s_waitcnt lgkmcnt(5)
	v_cvt_pk_bf16_f32 v4, v18, v19
	s_waitcnt lgkmcnt(4)
	v_cvt_pk_bf16_f32 v5, v20, v21
	v_lshl_add_u64 v[12:13], v[8:9], 0, v[12:13]
	global_store_dwordx4 v[12:13], v[2:5], off
	v_add_u32_e32 v10, 24, v10
	v_ashrrev_i32_e32 v11, 31, v10
	s_waitcnt lgkmcnt(3)
	v_cvt_pk_bf16_f32 v2, v22, v23
	s_waitcnt lgkmcnt(2)
	v_cvt_pk_bf16_f32 v3, v24, v25
	s_waitcnt lgkmcnt(1)
	v_cvt_pk_bf16_f32 v4, v26, v27
	v_lshlrev_b64 v[10:11], 11, v[10:11]
	s_waitcnt lgkmcnt(0)
	v_cvt_pk_bf16_f32 v5, v28, v29
	v_lshl_add_u64 v[6:7], v[8:9], 0, v[10:11]
	global_store_dwordx4 v[6:7], v[2:5], off
	s_waitcnt lgkmcnt(0)
	s_branch .LBB0_10
